# adaLN rewritten by hand without atomics (deterministic fixed-order reduction), same f32 math
# speedup vs baseline: 1.0005x; 1.0005x over previous
.LBB0_1094:
	v_readlane_b32 s0, v254, 63
	s_lshl_b32 s1, s0, 8
	s_add_i32 s1, s1, s67
	s_cmpk_ge_i32 s1, 1152
	s_cbranch_scc1 .LBB0_1101
	s_mul_hi_u32 s2, s1, 0xe38e39
	s_mul_i32 s3, s2, 0x120
	s_sub_i32 s3, s1, s3
	s_load_dwordx4 s[8:11], s[60:61], 0x38
	s_load_dwordx4 s[12:15], s[60:61], 0x48
	v_mbcnt_lo_u32_b32 v0, -1, 0
	v_mbcnt_hi_u32_b32 v0, -1, v0
	s_lshl_b32 s16, s0, 14
	v_lshlrev_b32_e32 v18, 4, v0
	v_lshl_add_u32 v19, v0, 6, s16
	s_waitcnt lgkmcnt(0)
	s_add_u32 s6, s8, 0x1000
	s_addc_u32 s7, s9, 0
	global_load_dwordx4 v[26:29], v18, s[10:11] offset:0
	global_load_dwordx4 v[42:45], v18, s[8:9] offset:0
	global_load_dwordx4 v[58:61], v18, s[6:7] offset:0
	global_load_dwordx4 v[30:33], v18, s[10:11] offset:1024
	global_load_dwordx4 v[46:49], v18, s[8:9] offset:1024
	global_load_dwordx4 v[62:65], v18, s[6:7] offset:1024
	global_load_dwordx4 v[34:37], v18, s[10:11] offset:2048
	global_load_dwordx4 v[50:53], v18, s[8:9] offset:2048
	global_load_dwordx4 v[66:69], v18, s[6:7] offset:2048
	global_load_dwordx4 v[38:41], v18, s[10:11] offset:3072
	global_load_dwordx4 v[54:57], v18, s[8:9] offset:3072
	global_load_dwordx4 v[70:73], v18, s[6:7] offset:3072
	s_waitcnt vmcnt(0)
	v_mul_f32_e32 v74, 0xbfb8aa3b, v26
	v_mul_f32_e32 v75, 0xbfb8aa3b, v27
	v_mul_f32_e32 v76, 0xbfb8aa3b, v28
	v_mul_f32_e32 v77, 0xbfb8aa3b, v29
	v_mul_f32_e32 v78, 0xbfb8aa3b, v30
	v_mul_f32_e32 v79, 0xbfb8aa3b, v31
	v_mul_f32_e32 v80, 0xbfb8aa3b, v32
	v_mul_f32_e32 v81, 0xbfb8aa3b, v33
	v_mul_f32_e32 v82, 0xbfb8aa3b, v34
	v_mul_f32_e32 v83, 0xbfb8aa3b, v35
	v_mul_f32_e32 v84, 0xbfb8aa3b, v36
	v_mul_f32_e32 v85, 0xbfb8aa3b, v37
	v_exp_f32_e32 v74, v74
	v_exp_f32_e32 v75, v75
	v_exp_f32_e32 v76, v76
	v_exp_f32_e32 v77, v77
	v_exp_f32_e32 v78, v78
	v_exp_f32_e32 v79, v79
	v_exp_f32_e32 v80, v80
	v_exp_f32_e32 v81, v81
	v_exp_f32_e32 v82, v82
	v_exp_f32_e32 v83, v83
	v_exp_f32_e32 v84, v84
	v_exp_f32_e32 v85, v85
	v_add_f32_e32 v74, 1.0, v74
	v_add_f32_e32 v75, 1.0, v75
	v_add_f32_e32 v76, 1.0, v76
	v_add_f32_e32 v77, 1.0, v77
	v_add_f32_e32 v78, 1.0, v78
	v_add_f32_e32 v79, 1.0, v79
	v_add_f32_e32 v80, 1.0, v80
	v_add_f32_e32 v81, 1.0, v81
	v_add_f32_e32 v82, 1.0, v82
	v_add_f32_e32 v83, 1.0, v83
	v_add_f32_e32 v84, 1.0, v84
	v_add_f32_e32 v85, 1.0, v85
	v_rcp_f32_e32 v74, v74
	v_rcp_f32_e32 v75, v75
	v_rcp_f32_e32 v76, v76
	v_rcp_f32_e32 v77, v77
	v_rcp_f32_e32 v78, v78
	v_rcp_f32_e32 v79, v79
	v_rcp_f32_e32 v80, v80
	v_rcp_f32_e32 v81, v81
	v_rcp_f32_e32 v82, v82
	v_rcp_f32_e32 v83, v83
	v_rcp_f32_e32 v84, v84
	v_rcp_f32_e32 v85, v85
	v_mul_f32_e32 v26, v26, v74
	v_mul_f32_e32 v27, v27, v75
	v_mul_f32_e32 v28, v28, v76
	v_mul_f32_e32 v29, v29, v77
	v_mul_f32_e32 v30, v30, v78
	v_mul_f32_e32 v31, v31, v79
	v_mul_f32_e32 v32, v32, v80
	v_mul_f32_e32 v33, v33, v81
	v_mul_f32_e32 v34, v34, v82
	v_mul_f32_e32 v35, v35, v83
	v_mul_f32_e32 v36, v36, v84
	v_mul_f32_e32 v37, v37, v85
	v_mul_f32_e32 v74, 0xbfb8aa3b, v38
	v_mul_f32_e32 v75, 0xbfb8aa3b, v39
	v_mul_f32_e32 v76, 0xbfb8aa3b, v40
	v_mul_f32_e32 v77, 0xbfb8aa3b, v41
	v_mul_f32_e32 v78, 0xbfb8aa3b, v42
	v_mul_f32_e32 v79, 0xbfb8aa3b, v43
	v_mul_f32_e32 v80, 0xbfb8aa3b, v44
	v_mul_f32_e32 v81, 0xbfb8aa3b, v45
	v_mul_f32_e32 v82, 0xbfb8aa3b, v46
	v_mul_f32_e32 v83, 0xbfb8aa3b, v47
	v_mul_f32_e32 v84, 0xbfb8aa3b, v48
	v_mul_f32_e32 v85, 0xbfb8aa3b, v49
	v_exp_f32_e32 v74, v74
	v_exp_f32_e32 v75, v75
	v_exp_f32_e32 v76, v76
	v_exp_f32_e32 v77, v77
	v_exp_f32_e32 v78, v78
	v_exp_f32_e32 v79, v79
	v_exp_f32_e32 v80, v80
	v_exp_f32_e32 v81, v81
	v_exp_f32_e32 v82, v82
	v_exp_f32_e32 v83, v83
	v_exp_f32_e32 v84, v84
	v_exp_f32_e32 v85, v85
	v_add_f32_e32 v74, 1.0, v74
	v_add_f32_e32 v75, 1.0, v75
	v_add_f32_e32 v76, 1.0, v76
	v_add_f32_e32 v77, 1.0, v77
	v_add_f32_e32 v78, 1.0, v78
	v_add_f32_e32 v79, 1.0, v79
	v_add_f32_e32 v80, 1.0, v80
	v_add_f32_e32 v81, 1.0, v81
	v_add_f32_e32 v82, 1.0, v82
	v_add_f32_e32 v83, 1.0, v83
	v_add_f32_e32 v84, 1.0, v84
	v_add_f32_e32 v85, 1.0, v85
	v_rcp_f32_e32 v74, v74
	v_rcp_f32_e32 v75, v75
	v_rcp_f32_e32 v76, v76
	v_rcp_f32_e32 v77, v77
	v_rcp_f32_e32 v78, v78
	v_rcp_f32_e32 v79, v79
	v_rcp_f32_e32 v80, v80
	v_rcp_f32_e32 v81, v81
	v_rcp_f32_e32 v82, v82
	v_rcp_f32_e32 v83, v83
	v_rcp_f32_e32 v84, v84
	v_rcp_f32_e32 v85, v85
	v_mul_f32_e32 v38, v38, v74
	v_mul_f32_e32 v39, v39, v75
	v_mul_f32_e32 v40, v40, v76
	v_mul_f32_e32 v41, v41, v77
	v_mul_f32_e32 v42, v42, v78
	v_mul_f32_e32 v43, v43, v79
	v_mul_f32_e32 v44, v44, v80
	v_mul_f32_e32 v45, v45, v81
	v_mul_f32_e32 v46, v46, v82
	v_mul_f32_e32 v47, v47, v83
	v_mul_f32_e32 v48, v48, v84
	v_mul_f32_e32 v49, v49, v85
	v_mul_f32_e32 v74, 0xbfb8aa3b, v50
	v_mul_f32_e32 v75, 0xbfb8aa3b, v51
	v_mul_f32_e32 v76, 0xbfb8aa3b, v52
	v_mul_f32_e32 v77, 0xbfb8aa3b, v53
	v_mul_f32_e32 v78, 0xbfb8aa3b, v54
	v_mul_f32_e32 v79, 0xbfb8aa3b, v55
	v_mul_f32_e32 v80, 0xbfb8aa3b, v56
	v_mul_f32_e32 v81, 0xbfb8aa3b, v57
	v_mul_f32_e32 v82, 0xbfb8aa3b, v58
	v_mul_f32_e32 v83, 0xbfb8aa3b, v59
	v_mul_f32_e32 v84, 0xbfb8aa3b, v60
	v_mul_f32_e32 v85, 0xbfb8aa3b, v61
	v_exp_f32_e32 v74, v74
	v_exp_f32_e32 v75, v75
	v_exp_f32_e32 v76, v76
	v_exp_f32_e32 v77, v77
	v_exp_f32_e32 v78, v78
	v_exp_f32_e32 v79, v79
	v_exp_f32_e32 v80, v80
	v_exp_f32_e32 v81, v81
	v_exp_f32_e32 v82, v82
	v_exp_f32_e32 v83, v83
	v_exp_f32_e32 v84, v84
	v_exp_f32_e32 v85, v85
	v_add_f32_e32 v74, 1.0, v74
	v_add_f32_e32 v75, 1.0, v75
	v_add_f32_e32 v76, 1.0, v76
	v_add_f32_e32 v77, 1.0, v77
	v_add_f32_e32 v78, 1.0, v78
	v_add_f32_e32 v79, 1.0, v79
	v_add_f32_e32 v80, 1.0, v80
	v_add_f32_e32 v81, 1.0, v81
	v_add_f32_e32 v82, 1.0, v82
	v_add_f32_e32 v83, 1.0, v83
	v_add_f32_e32 v84, 1.0, v84
	v_add_f32_e32 v85, 1.0, v85
	v_rcp_f32_e32 v74, v74
	v_rcp_f32_e32 v75, v75
	v_rcp_f32_e32 v76, v76
	v_rcp_f32_e32 v77, v77
	v_rcp_f32_e32 v78, v78
	v_rcp_f32_e32 v79, v79
	v_rcp_f32_e32 v80, v80
	v_rcp_f32_e32 v81, v81
	v_rcp_f32_e32 v82, v82
	v_rcp_f32_e32 v83, v83
	v_rcp_f32_e32 v84, v84
	v_rcp_f32_e32 v85, v85
	v_mul_f32_e32 v50, v50, v74
	v_mul_f32_e32 v51, v51, v75
	v_mul_f32_e32 v52, v52, v76
	v_mul_f32_e32 v53, v53, v77
	v_mul_f32_e32 v54, v54, v78
	v_mul_f32_e32 v55, v55, v79
	v_mul_f32_e32 v56, v56, v80
	v_mul_f32_e32 v57, v57, v81
	v_mul_f32_e32 v58, v58, v82
	v_mul_f32_e32 v59, v59, v83
	v_mul_f32_e32 v60, v60, v84
	v_mul_f32_e32 v61, v61, v85
	v_mul_f32_e32 v74, 0xbfb8aa3b, v62
	v_mul_f32_e32 v75, 0xbfb8aa3b, v63
	v_mul_f32_e32 v76, 0xbfb8aa3b, v64
	v_mul_f32_e32 v77, 0xbfb8aa3b, v65
	v_mul_f32_e32 v78, 0xbfb8aa3b, v66
	v_mul_f32_e32 v79, 0xbfb8aa3b, v67
	v_mul_f32_e32 v80, 0xbfb8aa3b, v68
	v_mul_f32_e32 v81, 0xbfb8aa3b, v69
	v_mul_f32_e32 v82, 0xbfb8aa3b, v70
	v_mul_f32_e32 v83, 0xbfb8aa3b, v71
	v_mul_f32_e32 v84, 0xbfb8aa3b, v72
	v_mul_f32_e32 v85, 0xbfb8aa3b, v73
	v_exp_f32_e32 v74, v74
	v_exp_f32_e32 v75, v75
	v_exp_f32_e32 v76, v76
	v_exp_f32_e32 v77, v77
	v_exp_f32_e32 v78, v78
	v_exp_f32_e32 v79, v79
	v_exp_f32_e32 v80, v80
	v_exp_f32_e32 v81, v81
	v_exp_f32_e32 v82, v82
	v_exp_f32_e32 v83, v83
	v_exp_f32_e32 v84, v84
	v_exp_f32_e32 v85, v85
	v_add_f32_e32 v74, 1.0, v74
	v_add_f32_e32 v75, 1.0, v75
	v_add_f32_e32 v76, 1.0, v76
	v_add_f32_e32 v77, 1.0, v77
	v_add_f32_e32 v78, 1.0, v78
	v_add_f32_e32 v79, 1.0, v79
	v_add_f32_e32 v80, 1.0, v80
	v_add_f32_e32 v81, 1.0, v81
	v_add_f32_e32 v82, 1.0, v82
	v_add_f32_e32 v83, 1.0, v83
	v_add_f32_e32 v84, 1.0, v84
	v_add_f32_e32 v85, 1.0, v85
	v_rcp_f32_e32 v74, v74
	v_rcp_f32_e32 v75, v75
	v_rcp_f32_e32 v76, v76
	v_rcp_f32_e32 v77, v77
	v_rcp_f32_e32 v78, v78
	v_rcp_f32_e32 v79, v79
	v_rcp_f32_e32 v80, v80
	v_rcp_f32_e32 v81, v81
	v_rcp_f32_e32 v82, v82
	v_rcp_f32_e32 v83, v83
	v_rcp_f32_e32 v84, v84
	v_rcp_f32_e32 v85, v85
	v_mul_f32_e32 v62, v62, v74
	v_mul_f32_e32 v63, v63, v75
	v_mul_f32_e32 v64, v64, v76
	v_mul_f32_e32 v65, v65, v77
	v_mul_f32_e32 v66, v66, v78
	v_mul_f32_e32 v67, v67, v79
	v_mul_f32_e32 v68, v68, v80
	v_mul_f32_e32 v69, v69, v81
	v_mul_f32_e32 v70, v70, v82
	v_mul_f32_e32 v71, v71, v83
	v_mul_f32_e32 v72, v72, v84
	v_mul_f32_e32 v73, v73, v85
	v_mov_b32_e32 v90, v26
	v_mov_b32_e32 v91, v42
	v_mov_b32_e32 v92, v58
	v_mov_b32_e32 v93, 0
	ds_write_b128 v19, v[90:93] offset:0
	v_mov_b32_e32 v94, v27
	v_mov_b32_e32 v95, v43
	v_mov_b32_e32 v96, v59
	v_mov_b32_e32 v97, 0
	ds_write_b128 v19, v[94:97] offset:16
	v_mov_b32_e32 v90, v28
	v_mov_b32_e32 v91, v44
	v_mov_b32_e32 v92, v60
	v_mov_b32_e32 v93, 0
	ds_write_b128 v19, v[90:93] offset:32
	v_mov_b32_e32 v94, v29
	v_mov_b32_e32 v95, v45
	v_mov_b32_e32 v96, v61
	v_mov_b32_e32 v97, 0
	ds_write_b128 v19, v[94:97] offset:48
	v_mov_b32_e32 v90, v30
	v_mov_b32_e32 v91, v46
	v_mov_b32_e32 v92, v62
	v_mov_b32_e32 v93, 0
	ds_write_b128 v19, v[90:93] offset:4096
	v_mov_b32_e32 v94, v31
	v_mov_b32_e32 v95, v47
	v_mov_b32_e32 v96, v63
	v_mov_b32_e32 v97, 0
	ds_write_b128 v19, v[94:97] offset:4112
	v_mov_b32_e32 v90, v32
	v_mov_b32_e32 v91, v48
	v_mov_b32_e32 v92, v64
	v_mov_b32_e32 v93, 0
	ds_write_b128 v19, v[90:93] offset:4128
	v_mov_b32_e32 v94, v33
	v_mov_b32_e32 v95, v49
	v_mov_b32_e32 v96, v65
	v_mov_b32_e32 v97, 0
	ds_write_b128 v19, v[94:97] offset:4144
	v_mov_b32_e32 v90, v34
	v_mov_b32_e32 v91, v50
	v_mov_b32_e32 v92, v66
	v_mov_b32_e32 v93, 0
	ds_write_b128 v19, v[90:93] offset:8192
	v_mov_b32_e32 v94, v35
	v_mov_b32_e32 v95, v51
	v_mov_b32_e32 v96, v67
	v_mov_b32_e32 v97, 0
	ds_write_b128 v19, v[94:97] offset:8208
	v_mov_b32_e32 v90, v36
	v_mov_b32_e32 v91, v52
	v_mov_b32_e32 v92, v68
	v_mov_b32_e32 v93, 0
	ds_write_b128 v19, v[90:93] offset:8224
	v_mov_b32_e32 v94, v37
	v_mov_b32_e32 v95, v53
	v_mov_b32_e32 v96, v69
	v_mov_b32_e32 v97, 0
	ds_write_b128 v19, v[94:97] offset:8240
	v_mov_b32_e32 v90, v38
	v_mov_b32_e32 v91, v54
	v_mov_b32_e32 v92, v70
	v_mov_b32_e32 v93, 0
	ds_write_b128 v19, v[90:93] offset:12288
	v_mov_b32_e32 v94, v39
	v_mov_b32_e32 v95, v55
	v_mov_b32_e32 v96, v71
	v_mov_b32_e32 v97, 0
	ds_write_b128 v19, v[94:97] offset:12304
	v_mov_b32_e32 v90, v40
	v_mov_b32_e32 v91, v56
	v_mov_b32_e32 v92, v72
	v_mov_b32_e32 v93, 0
	ds_write_b128 v19, v[90:93] offset:12320
	v_mov_b32_e32 v94, v41
	v_mov_b32_e32 v95, v57
	v_mov_b32_e32 v96, v73
	v_mov_b32_e32 v97, 0
	ds_write_b128 v19, v[94:97] offset:12336
	s_waitcnt lgkmcnt(0)
	v_lshrrev_b32_e32 v20, 3, v0
	v_and_b32_e32 v21, 7, v0
	v_mul_u32_u24_e32 v22, 0x9000, v20
	v_lshl_add_u32 v22, v21, 4, v22
	s_mul_i32 s17, s2, 0x2400000
	s_lshl_b32 s18, s3, 7
	s_add_u32 s17, s17, s18
	s_add_u32 s12, s12, s17
	s_addc_u32 s13, s13, 0
	v_lshl_add_u32 v23, v20, 4, s16
	v_mov_b32_e32 v2, 0
	v_mov_b32_e32 v3, 0
	v_mov_b32_e32 v4, 0
	v_mov_b32_e32 v5, 0
	v_mov_b32_e32 v6, 0
	v_mov_b32_e32 v7, 0
	v_mov_b32_e32 v8, 0
	v_mov_b32_e32 v9, 0
	v_mov_b32_e32 v10, 0
	v_mov_b32_e32 v11, 0
	v_mov_b32_e32 v12, 0
	v_mov_b32_e32 v13, 0
	s_mov_b32 s19, 8
.Lada_blk:
	global_load_dwordx4 v[26:29], v22, s[12:13] nt
	s_add_u32 s12, s12, 0x48000
	s_addc_u32 s13, s13, 0
	global_load_dwordx4 v[30:33], v22, s[12:13] nt
	s_add_u32 s12, s12, 0x48000
	s_addc_u32 s13, s13, 0
	global_load_dwordx4 v[34:37], v22, s[12:13] nt
	s_add_u32 s12, s12, 0x48000
	s_addc_u32 s13, s13, 0
	global_load_dwordx4 v[38:41], v22, s[12:13] nt
	s_add_u32 s12, s12, 0x48000
	s_addc_u32 s13, s13, 0
	global_load_dwordx4 v[42:45], v22, s[12:13] nt
	s_add_u32 s12, s12, 0x48000
	s_addc_u32 s13, s13, 0
	global_load_dwordx4 v[46:49], v22, s[12:13] nt
	s_add_u32 s12, s12, 0x48000
	s_addc_u32 s13, s13, 0
	global_load_dwordx4 v[50:53], v22, s[12:13] nt
	s_add_u32 s12, s12, 0x48000
	s_addc_u32 s13, s13, 0
	global_load_dwordx4 v[54:57], v22, s[12:13] nt
	s_add_u32 s12, s12, 0x48000
	s_addc_u32 s13, s13, 0
	global_load_dwordx4 v[58:61], v22, s[12:13] nt
	s_add_u32 s12, s12, 0x48000
	s_addc_u32 s13, s13, 0
	global_load_dwordx4 v[62:65], v22, s[12:13] nt
	s_add_u32 s12, s12, 0x48000
	s_addc_u32 s13, s13, 0
	global_load_dwordx4 v[66:69], v22, s[12:13] nt
	s_add_u32 s12, s12, 0x48000
	s_addc_u32 s13, s13, 0
	global_load_dwordx4 v[70:73], v22, s[12:13] nt
	s_add_u32 s12, s12, 0x48000
	s_addc_u32 s13, s13, 0
	global_load_dwordx4 v[74:77], v22, s[12:13] nt
	s_add_u32 s12, s12, 0x48000
	s_addc_u32 s13, s13, 0
	global_load_dwordx4 v[78:81], v22, s[12:13] nt
	s_add_u32 s12, s12, 0x48000
	s_addc_u32 s13, s13, 0
	global_load_dwordx4 v[82:85], v22, s[12:13] nt
	s_add_u32 s12, s12, 0x48000
	s_addc_u32 s13, s13, 0
	global_load_dwordx4 v[86:89], v22, s[12:13] nt
	s_add_u32 s12, s12, 0x48000
	s_addc_u32 s13, s13, 0
	ds_read_b128 v[14:17], v23
	ds_read_b128 v[90:93], v23 offset:128
	s_waitcnt vmcnt(15) lgkmcnt(1)
	v_fmac_f32_e32 v2, v26, v14
	v_fmac_f32_e32 v3, v27, v14
	v_fmac_f32_e32 v4, v28, v14
	v_fmac_f32_e32 v5, v29, v14
	v_fmac_f32_e32 v6, v26, v15
	v_fmac_f32_e32 v7, v27, v15
	v_fmac_f32_e32 v8, v28, v15
	v_fmac_f32_e32 v9, v29, v15
	v_fmac_f32_e32 v10, v26, v16
	v_fmac_f32_e32 v11, v27, v16
	v_fmac_f32_e32 v12, v28, v16
	v_fmac_f32_e32 v13, v29, v16
	ds_read_b128 v[14:17], v23 offset:256
	s_waitcnt vmcnt(14) lgkmcnt(1)
	v_fmac_f32_e32 v2, v30, v90
	v_fmac_f32_e32 v3, v31, v90
	v_fmac_f32_e32 v4, v32, v90
	v_fmac_f32_e32 v5, v33, v90
	v_fmac_f32_e32 v6, v30, v91
	v_fmac_f32_e32 v7, v31, v91
	v_fmac_f32_e32 v8, v32, v91
	v_fmac_f32_e32 v9, v33, v91
	v_fmac_f32_e32 v10, v30, v92
	v_fmac_f32_e32 v11, v31, v92
	v_fmac_f32_e32 v12, v32, v92
	v_fmac_f32_e32 v13, v33, v92
	ds_read_b128 v[90:93], v23 offset:384
	s_waitcnt vmcnt(13) lgkmcnt(1)
	v_fmac_f32_e32 v2, v34, v14
	v_fmac_f32_e32 v3, v35, v14
	v_fmac_f32_e32 v4, v36, v14
	v_fmac_f32_e32 v5, v37, v14
	v_fmac_f32_e32 v6, v34, v15
	v_fmac_f32_e32 v7, v35, v15
	v_fmac_f32_e32 v8, v36, v15
	v_fmac_f32_e32 v9, v37, v15
	v_fmac_f32_e32 v10, v34, v16
	v_fmac_f32_e32 v11, v35, v16
	v_fmac_f32_e32 v12, v36, v16
	v_fmac_f32_e32 v13, v37, v16
	ds_read_b128 v[14:17], v23 offset:512
	s_waitcnt vmcnt(12) lgkmcnt(1)
	v_fmac_f32_e32 v2, v38, v90
	v_fmac_f32_e32 v3, v39, v90
	v_fmac_f32_e32 v4, v40, v90
	v_fmac_f32_e32 v5, v41, v90
	v_fmac_f32_e32 v6, v38, v91
	v_fmac_f32_e32 v7, v39, v91
	v_fmac_f32_e32 v8, v40, v91
	v_fmac_f32_e32 v9, v41, v91
	v_fmac_f32_e32 v10, v38, v92
	v_fmac_f32_e32 v11, v39, v92
	v_fmac_f32_e32 v12, v40, v92
	v_fmac_f32_e32 v13, v41, v92
	ds_read_b128 v[90:93], v23 offset:640
	s_waitcnt vmcnt(11) lgkmcnt(1)
	v_fmac_f32_e32 v2, v42, v14
	v_fmac_f32_e32 v3, v43, v14
	v_fmac_f32_e32 v4, v44, v14
	v_fmac_f32_e32 v5, v45, v14
	v_fmac_f32_e32 v6, v42, v15
	v_fmac_f32_e32 v7, v43, v15
	v_fmac_f32_e32 v8, v44, v15
	v_fmac_f32_e32 v9, v45, v15
	v_fmac_f32_e32 v10, v42, v16
	v_fmac_f32_e32 v11, v43, v16
	v_fmac_f32_e32 v12, v44, v16
	v_fmac_f32_e32 v13, v45, v16
	ds_read_b128 v[14:17], v23 offset:768
	s_waitcnt vmcnt(10) lgkmcnt(1)
	v_fmac_f32_e32 v2, v46, v90
	v_fmac_f32_e32 v3, v47, v90
	v_fmac_f32_e32 v4, v48, v90
	v_fmac_f32_e32 v5, v49, v90
	v_fmac_f32_e32 v6, v46, v91
	v_fmac_f32_e32 v7, v47, v91
	v_fmac_f32_e32 v8, v48, v91
	v_fmac_f32_e32 v9, v49, v91
	v_fmac_f32_e32 v10, v46, v92
	v_fmac_f32_e32 v11, v47, v92
	v_fmac_f32_e32 v12, v48, v92
	v_fmac_f32_e32 v13, v49, v92
	ds_read_b128 v[90:93], v23 offset:896
	s_waitcnt vmcnt(9) lgkmcnt(1)
	v_fmac_f32_e32 v2, v50, v14
	v_fmac_f32_e32 v3, v51, v14
	v_fmac_f32_e32 v4, v52, v14
	v_fmac_f32_e32 v5, v53, v14
	v_fmac_f32_e32 v6, v50, v15
	v_fmac_f32_e32 v7, v51, v15
	v_fmac_f32_e32 v8, v52, v15
	v_fmac_f32_e32 v9, v53, v15
	v_fmac_f32_e32 v10, v50, v16
	v_fmac_f32_e32 v11, v51, v16
	v_fmac_f32_e32 v12, v52, v16
	v_fmac_f32_e32 v13, v53, v16
	ds_read_b128 v[14:17], v23 offset:1024
	s_waitcnt vmcnt(8) lgkmcnt(1)
	v_fmac_f32_e32 v2, v54, v90
	v_fmac_f32_e32 v3, v55, v90
	v_fmac_f32_e32 v4, v56, v90
	v_fmac_f32_e32 v5, v57, v90
	v_fmac_f32_e32 v6, v54, v91
	v_fmac_f32_e32 v7, v55, v91
	v_fmac_f32_e32 v8, v56, v91
	v_fmac_f32_e32 v9, v57, v91
	v_fmac_f32_e32 v10, v54, v92
	v_fmac_f32_e32 v11, v55, v92
	v_fmac_f32_e32 v12, v56, v92
	v_fmac_f32_e32 v13, v57, v92
	ds_read_b128 v[90:93], v23 offset:1152
	s_waitcnt vmcnt(7) lgkmcnt(1)
	v_fmac_f32_e32 v2, v58, v14
	v_fmac_f32_e32 v3, v59, v14
	v_fmac_f32_e32 v4, v60, v14
	v_fmac_f32_e32 v5, v61, v14
	v_fmac_f32_e32 v6, v58, v15
	v_fmac_f32_e32 v7, v59, v15
	v_fmac_f32_e32 v8, v60, v15
	v_fmac_f32_e32 v9, v61, v15
	v_fmac_f32_e32 v10, v58, v16
	v_fmac_f32_e32 v11, v59, v16
	v_fmac_f32_e32 v12, v60, v16
	v_fmac_f32_e32 v13, v61, v16
	ds_read_b128 v[14:17], v23 offset:1280
	s_waitcnt vmcnt(6) lgkmcnt(1)
	v_fmac_f32_e32 v2, v62, v90
	v_fmac_f32_e32 v3, v63, v90
	v_fmac_f32_e32 v4, v64, v90
	v_fmac_f32_e32 v5, v65, v90
	v_fmac_f32_e32 v6, v62, v91
	v_fmac_f32_e32 v7, v63, v91
	v_fmac_f32_e32 v8, v64, v91
	v_fmac_f32_e32 v9, v65, v91
	v_fmac_f32_e32 v10, v62, v92
	v_fmac_f32_e32 v11, v63, v92
	v_fmac_f32_e32 v12, v64, v92
	v_fmac_f32_e32 v13, v65, v92
	ds_read_b128 v[90:93], v23 offset:1408
	s_waitcnt vmcnt(5) lgkmcnt(1)
	v_fmac_f32_e32 v2, v66, v14
	v_fmac_f32_e32 v3, v67, v14
	v_fmac_f32_e32 v4, v68, v14
	v_fmac_f32_e32 v5, v69, v14
	v_fmac_f32_e32 v6, v66, v15
	v_fmac_f32_e32 v7, v67, v15
	v_fmac_f32_e32 v8, v68, v15
	v_fmac_f32_e32 v9, v69, v15
	v_fmac_f32_e32 v10, v66, v16
	v_fmac_f32_e32 v11, v67, v16
	v_fmac_f32_e32 v12, v68, v16
	v_fmac_f32_e32 v13, v69, v16
	ds_read_b128 v[14:17], v23 offset:1536
	s_waitcnt vmcnt(4) lgkmcnt(1)
	v_fmac_f32_e32 v2, v70, v90
	v_fmac_f32_e32 v3, v71, v90
	v_fmac_f32_e32 v4, v72, v90
	v_fmac_f32_e32 v5, v73, v90
	v_fmac_f32_e32 v6, v70, v91
	v_fmac_f32_e32 v7, v71, v91
	v_fmac_f32_e32 v8, v72, v91
	v_fmac_f32_e32 v9, v73, v91
	v_fmac_f32_e32 v10, v70, v92
	v_fmac_f32_e32 v11, v71, v92
	v_fmac_f32_e32 v12, v72, v92
	v_fmac_f32_e32 v13, v73, v92
	ds_read_b128 v[90:93], v23 offset:1664
	s_waitcnt vmcnt(3) lgkmcnt(1)
	v_fmac_f32_e32 v2, v74, v14
	v_fmac_f32_e32 v3, v75, v14
	v_fmac_f32_e32 v4, v76, v14
	v_fmac_f32_e32 v5, v77, v14
	v_fmac_f32_e32 v6, v74, v15
	v_fmac_f32_e32 v7, v75, v15
	v_fmac_f32_e32 v8, v76, v15
	v_fmac_f32_e32 v9, v77, v15
	v_fmac_f32_e32 v10, v74, v16
	v_fmac_f32_e32 v11, v75, v16
	v_fmac_f32_e32 v12, v76, v16
	v_fmac_f32_e32 v13, v77, v16
	ds_read_b128 v[14:17], v23 offset:1792
	s_waitcnt vmcnt(2) lgkmcnt(1)
	v_fmac_f32_e32 v2, v78, v90
	v_fmac_f32_e32 v3, v79, v90
	v_fmac_f32_e32 v4, v80, v90
	v_fmac_f32_e32 v5, v81, v90
	v_fmac_f32_e32 v6, v78, v91
	v_fmac_f32_e32 v7, v79, v91
	v_fmac_f32_e32 v8, v80, v91
	v_fmac_f32_e32 v9, v81, v91
	v_fmac_f32_e32 v10, v78, v92
	v_fmac_f32_e32 v11, v79, v92
	v_fmac_f32_e32 v12, v80, v92
	v_fmac_f32_e32 v13, v81, v92
	ds_read_b128 v[90:93], v23 offset:1920
	s_waitcnt vmcnt(1) lgkmcnt(1)
	v_fmac_f32_e32 v2, v82, v14
	v_fmac_f32_e32 v3, v83, v14
	v_fmac_f32_e32 v4, v84, v14
	v_fmac_f32_e32 v5, v85, v14
	v_fmac_f32_e32 v6, v82, v15
	v_fmac_f32_e32 v7, v83, v15
	v_fmac_f32_e32 v8, v84, v15
	v_fmac_f32_e32 v9, v85, v15
	v_fmac_f32_e32 v10, v82, v16
	v_fmac_f32_e32 v11, v83, v16
	v_fmac_f32_e32 v12, v84, v16
	v_fmac_f32_e32 v13, v85, v16
	s_waitcnt vmcnt(0) lgkmcnt(0)
	v_fmac_f32_e32 v2, v86, v90
	v_fmac_f32_e32 v3, v87, v90
	v_fmac_f32_e32 v4, v88, v90
	v_fmac_f32_e32 v5, v89, v90
	v_fmac_f32_e32 v6, v86, v91
	v_fmac_f32_e32 v7, v87, v91
	v_fmac_f32_e32 v8, v88, v91
	v_fmac_f32_e32 v9, v89, v91
	v_fmac_f32_e32 v10, v86, v92
	v_fmac_f32_e32 v11, v87, v92
	v_fmac_f32_e32 v12, v88, v92
	v_fmac_f32_e32 v13, v89, v92
	v_add_u32_e32 v23, 0x800, v23
	s_add_i32 s19, s19, -1
	s_cmp_lg_u32 s19, 0
	s_cbranch_scc1 .Lada_blk
	s_mul_i32 s17, s2, 0x9000
	s_add_u32 s14, s14, s17
	s_addc_u32 s15, s15, 0
	s_add_u32 s14, s14, s18
	s_addc_u32 s15, s15, 0
	v_lshlrev_b32_e32 v18, 4, v21
	global_load_dwordx4 v[14:17], v18, s[14:15]
	s_nop 1
	v_add_f32_dpp v2, v2, v2 row_ror:8 row_mask:0xf bank_mask:0xf
	v_add_f32_dpp v3, v3, v3 row_ror:8 row_mask:0xf bank_mask:0xf
	v_add_f32_dpp v4, v4, v4 row_ror:8 row_mask:0xf bank_mask:0xf
	v_add_f32_dpp v5, v5, v5 row_ror:8 row_mask:0xf bank_mask:0xf
	v_add_f32_dpp v6, v6, v6 row_ror:8 row_mask:0xf bank_mask:0xf
	v_add_f32_dpp v7, v7, v7 row_ror:8 row_mask:0xf bank_mask:0xf
	v_add_f32_dpp v8, v8, v8 row_ror:8 row_mask:0xf bank_mask:0xf
	v_add_f32_dpp v9, v9, v9 row_ror:8 row_mask:0xf bank_mask:0xf
	v_add_f32_dpp v10, v10, v10 row_ror:8 row_mask:0xf bank_mask:0xf
	v_add_f32_dpp v11, v11, v11 row_ror:8 row_mask:0xf bank_mask:0xf
	v_add_f32_dpp v12, v12, v12 row_ror:8 row_mask:0xf bank_mask:0xf
	v_add_f32_dpp v13, v13, v13 row_ror:8 row_mask:0xf bank_mask:0xf
	v_mov_b32_e32 v26, v2
	v_mov_b32_e32 v27, v3
	v_mov_b32_e32 v28, v4
	v_mov_b32_e32 v29, v5
	v_mov_b32_e32 v30, v6
	v_mov_b32_e32 v31, v7
	v_mov_b32_e32 v32, v8
	v_mov_b32_e32 v33, v9
	v_mov_b32_e32 v34, v10
	v_mov_b32_e32 v35, v11
	v_mov_b32_e32 v36, v12
	v_mov_b32_e32 v37, v13
	s_nop 1
	v_permlane16_swap_b32_e32 v26, v2
	v_permlane16_swap_b32_e32 v27, v3
	v_permlane16_swap_b32_e32 v28, v4
	v_permlane16_swap_b32_e32 v29, v5
	v_permlane16_swap_b32_e32 v30, v6
	v_permlane16_swap_b32_e32 v31, v7
	v_permlane16_swap_b32_e32 v32, v8
	v_permlane16_swap_b32_e32 v33, v9
	v_permlane16_swap_b32_e32 v34, v10
	v_permlane16_swap_b32_e32 v35, v11
	v_permlane16_swap_b32_e32 v36, v12
	v_permlane16_swap_b32_e32 v37, v13
	v_add_f32_e32 v2, v2, v26
	v_add_f32_e32 v3, v3, v27
	v_add_f32_e32 v4, v4, v28
	v_add_f32_e32 v5, v5, v29
	v_add_f32_e32 v6, v6, v30
	v_add_f32_e32 v7, v7, v31
	v_add_f32_e32 v8, v8, v32
	v_add_f32_e32 v9, v9, v33
	v_add_f32_e32 v10, v10, v34
	v_add_f32_e32 v11, v11, v35
	v_add_f32_e32 v12, v12, v36
	v_add_f32_e32 v13, v13, v37
	v_mov_b32_e32 v26, v2
	v_mov_b32_e32 v27, v3
	v_mov_b32_e32 v28, v4
	v_mov_b32_e32 v29, v5
	v_mov_b32_e32 v30, v6
	v_mov_b32_e32 v31, v7
	v_mov_b32_e32 v32, v8
	v_mov_b32_e32 v33, v9
	v_mov_b32_e32 v34, v10
	v_mov_b32_e32 v35, v11
	v_mov_b32_e32 v36, v12
	v_mov_b32_e32 v37, v13
	s_nop 1
	v_permlane32_swap_b32_e32 v26, v2
	v_permlane32_swap_b32_e32 v27, v3
	v_permlane32_swap_b32_e32 v28, v4
	v_permlane32_swap_b32_e32 v29, v5
	v_permlane32_swap_b32_e32 v30, v6
	v_permlane32_swap_b32_e32 v31, v7
	v_permlane32_swap_b32_e32 v32, v8
	v_permlane32_swap_b32_e32 v33, v9
	v_permlane32_swap_b32_e32 v34, v10
	v_permlane32_swap_b32_e32 v35, v11
	v_permlane32_swap_b32_e32 v36, v12
	v_permlane32_swap_b32_e32 v37, v13
	v_add_f32_e32 v2, v2, v26
	v_add_f32_e32 v3, v3, v27
	v_add_f32_e32 v4, v4, v28
	v_add_f32_e32 v5, v5, v29
	v_add_f32_e32 v6, v6, v30
	v_add_f32_e32 v7, v7, v31
	v_add_f32_e32 v8, v8, v32
	v_add_f32_e32 v9, v9, v33
	v_add_f32_e32 v10, v10, v34
	v_add_f32_e32 v11, v11, v35
	v_add_f32_e32 v12, v12, v36
	v_add_f32_e32 v13, v13, v37
	s_waitcnt vmcnt(0)
	v_add_f32_e32 v2, v2, v14
	v_add_f32_e32 v3, v3, v15
	v_add_f32_e32 v4, v4, v16
	v_add_f32_e32 v5, v5, v17
	v_add_f32_e32 v6, v6, v14
	v_add_f32_e32 v7, v7, v15
	v_add_f32_e32 v8, v8, v16
	v_add_f32_e32 v9, v9, v17
	v_add_f32_e32 v10, v10, v14
	v_add_f32_e32 v11, v11, v15
	v_add_f32_e32 v12, v12, v16
	v_add_f32_e32 v13, v13, v17
	v_readlane_b32 s8, v255, 7
	v_readlane_b32 s9, v255, 8
	s_mul_i32 s17, s2, 0x1b000
	s_add_u32 s17, s17, s18
	s_add_u32 s17, s17, 0x100000
	s_add_u32 s8, s8, s17
	s_addc_u32 s9, s9, 0
	s_add_u32 s10, s8, 0x9000
	s_addc_u32 s11, s9, 0
	s_add_u32 s12, s8, 0x12000
	s_addc_u32 s13, s9, 0
	s_mov_b64 exec, 0xff
	global_store_dwordx4 v18, v[2:5], s[8:9]
	global_store_dwordx4 v18, v[6:9], s[10:11]
	global_store_dwordx4 v18, v[10:13], s[12:13]
	s_mov_b64 exec, -1
